# plus flat->global addressing for all plain loads/stores
# baseline (speedup 1.0000x reference)
.LBB0_949:
	s_or_b64 exec, exec, s[10:11]
	v_add_co_u32_e32 v86, vcc, s63, v128
	v_pk_mul_f32 v[94:95], v[6:7], v[76:77]
	s_nop 0
	v_addc_co_u32_e32 v87, vcc, 0, v129, vcc
	global_load_dwordx2 v[88:89], v[86:87], off offset:2560
	v_lshl_add_u64 v[178:179], v[116:117], 0, s[100:101]
	v_lshl_add_u64 v[180:181], v[110:111], 0, s[100:101]
	v_lshl_add_u64 v[182:183], v[100:101], 0, s[100:101]
	global_load_dwordx2 v[184:185], v[178:179], off offset:2560
	global_load_dwordx2 v[186:187], v[180:181], off offset:2560
	global_load_dwordx2 v[188:189], v[182:183], off offset:2560
	v_pk_mul_f32 v[96:97], v[4:5], v[72:73]
	v_lshlrev_b32_e32 v62, 16, v148
	v_and_b32_e32 v63, 0xffff0000, v148
	v_lshlrev_b32_e32 v64, 16, v149
	v_and_b32_e32 v65, 0xffff0000, v149
	v_pk_mul_f32 v[106:107], v[18:19], v[80:81]
	v_pk_mul_f32 v[108:109], v[16:17], v[78:79]
	v_pk_fma_f32 v[94:95], v[2:3], v[144:145], v[94:95]
	v_pk_fma_f32 v[96:97], v[0:1], v[142:143], v[96:97]
	v_lshlrev_b32_e32 v66, 16, v152
	v_and_b32_e32 v67, 0xffff0000, v152
	v_lshlrev_b32_e32 v68, 16, v153
	v_and_b32_e32 v69, 0xffff0000, v153
	v_lshlrev_b32_e32 v70, 16, v150
	v_and_b32_e32 v71, 0xffff0000, v150
	v_lshlrev_b32_e32 v74, 16, v151
	v_and_b32_e32 v75, 0xffff0000, v151
	v_pk_mul_f32 v[148:149], v[30:31], v[84:85]
	v_pk_mul_f32 v[150:151], v[28:29], v[82:83]
	v_pk_fma_f32 v[106:107], v[14:15], v[136:137], v[106:107]
	v_pk_fma_f32 v[108:109], v[12:13], v[134:135], v[108:109]
	v_pk_fma_f32 v[94:95], v[10:11], v[64:65], v[94:95]
	v_pk_fma_f32 v[96:97], v[8:9], v[62:63], v[96:97]
	v_pk_fma_f32 v[142:143], v[26:27], v[126:127], v[148:149]
	v_pk_fma_f32 v[144:145], v[24:25], v[122:123], v[150:151]
	v_pk_fma_f32 v[106:107], v[22:23], v[68:69], v[106:107]
	v_pk_fma_f32 v[108:109], v[20:21], v[66:67], v[108:109]
	v_pk_add_f32 v[94:95], v[38:39], v[94:95]
	v_pk_add_f32 v[96:97], v[36:37], v[96:97]
	v_pk_fma_f32 v[142:143], v[34:35], v[74:75], v[142:143]
	v_pk_fma_f32 v[144:145], v[32:33], v[70:71], v[144:145]
	v_pk_add_f32 v[94:95], v[106:107], v[94:95]
	v_pk_add_f32 v[96:97], v[108:109], v[96:97]
	v_pk_add_f32 v[94:95], v[142:143], v[94:95]
	v_pk_add_f32 v[96:97], v[144:145], v[96:97]
	v_mov_b64_e32 v[128:129], s[28:29]
	v_pk_mul_f32 v[106:107], v[94:95], v[94:95]
	v_pk_mul_f32 v[108:109], v[96:97], v[96:97]
	v_pk_fma_f32 v[106:107], v[106:107], s[26:27], v[128:129] op_sel_hi:[1,0,0] neg_lo:[1,0,0] neg_hi:[1,0,0]
	v_pk_fma_f32 v[108:109], v[108:109], s[26:27], v[128:129] op_sel_hi:[1,0,0] neg_lo:[1,0,0] neg_hi:[1,0,0]
	v_pk_mul_f32 v[106:107], v[94:95], v[106:107]
	v_pk_mul_f32 v[108:109], v[96:97], v[108:109]
	v_exp_f32_e32 v106, v106
	v_exp_f32_e32 v108, v108
	v_exp_f32_e32 v109, v109
	v_exp_f32_e32 v107, v107
	v_add_co_u32_e32 v116, vcc, s63, v116
	v_pk_add_f32 v[108:109], v[108:109], 1.0 op_sel_hi:[1,0]
	v_pk_add_f32 v[106:107], v[106:107], 1.0 op_sel_hi:[1,0]
	v_rcp_f32_e32 v108, v108
	v_rcp_f32_e32 v109, v109
	v_rcp_f32_e32 v106, v106
	v_rcp_f32_e32 v107, v107
	v_addc_co_u32_e32 v117, vcc, 0, v117, vcc
	v_pk_mul_f32 v[96:97], v[96:97], v[108:109]
	v_pk_mul_f32 v[94:95], v[94:95], v[106:107]
	v_pk_mul_f32 v[108:109], v[18:19], v[84:85]
	v_pk_mul_f32 v[142:143], v[16:17], v[82:83]
	v_pk_mul_f32 v[144:145], v[30:31], v[92:93]
	v_pk_fma_f32 v[108:109], v[14:15], v[126:127], v[108:109]
	v_add_co_u32_e32 v110, vcc, s63, v110
	v_pk_fma_f32 v[108:109], v[22:23], v[74:75], v[108:109]
	s_nop 0
	v_addc_co_u32_e32 v111, vcc, 0, v111, vcc
	v_add_co_u32_e32 v100, vcc, s63, v100
	s_waitcnt vmcnt(0) lgkmcnt(0)
	v_mov_b64_e32 v[148:149], v[158:159]
	v_addc_co_u32_e32 v101, vcc, 0, v101, vcc
	v_mov_b64_e32 v[152:153], v[154:155]
	v_mov_b64_e32 v[150:151], v[156:157]
	v_lshlrev_b32_e32 v43, 16, v88
	v_and_b32_e32 v88, 0xffff0000, v88
	v_lshlrev_b32_e32 v106, 16, v89
	v_and_b32_e32 v89, 0xffff0000, v89
	v_mul_f32_e32 v88, v97, v88
	v_mul_f32_e32 v89, v95, v89
	v_mul_f32_e32 v43, v96, v43
	v_mul_f32_e32 v94, v94, v106
	v_cvt_pk_bf16_f32 v88, v43, v88
	v_cvt_pk_bf16_f32 v89, v94, v89
	global_store_dwordx2 v[86:87], v[88:89], off offset:2560
	v_mov_b64_e32 v[94:95], v[184:185]
	v_pk_mul_f32 v[96:97], v[6:7], v[80:81]
	v_pk_mul_f32 v[106:107], v[4:5], v[78:79]
	v_pk_fma_f32 v[96:97], v[2:3], v[136:137], v[96:97]
	v_pk_fma_f32 v[106:107], v[0:1], v[134:135], v[106:107]
	v_lshlrev_b32_e32 v86, 16, v146
	v_and_b32_e32 v87, 0xffff0000, v146
	v_lshlrev_b32_e32 v88, 16, v147
	v_and_b32_e32 v89, 0xffff0000, v147
	v_pk_mul_f32 v[146:147], v[28:29], v[90:91]
	v_pk_fma_f32 v[134:135], v[12:13], v[122:123], v[142:143]
	v_pk_fma_f32 v[96:97], v[10:11], v[68:69], v[96:97]
	v_pk_fma_f32 v[106:107], v[8:9], v[66:67], v[106:107]
	v_pk_fma_f32 v[136:137], v[26:27], v[120:121], v[144:145]
	v_pk_fma_f32 v[142:143], v[24:25], v[118:119], v[146:147]
	v_pk_fma_f32 v[134:135], v[20:21], v[70:71], v[134:135]
	v_pk_add_f32 v[96:97], v[38:39], v[96:97]
	v_pk_add_f32 v[106:107], v[36:37], v[106:107]
	v_pk_fma_f32 v[136:137], v[34:35], v[88:89], v[136:137]
	v_pk_fma_f32 v[142:143], v[32:33], v[86:87], v[142:143]
	v_pk_add_f32 v[96:97], v[108:109], v[96:97]
	v_pk_add_f32 v[106:107], v[134:135], v[106:107]
	v_pk_add_f32 v[96:97], v[136:137], v[96:97]
	v_pk_add_f32 v[106:107], v[142:143], v[106:107]
	v_pk_mul_f32 v[108:109], v[96:97], v[96:97]
	v_pk_mul_f32 v[134:135], v[106:107], v[106:107]
	v_pk_fma_f32 v[108:109], v[108:109], s[26:27], v[128:129] op_sel_hi:[1,0,0] neg_lo:[1,0,0] neg_hi:[1,0,0]
	v_pk_fma_f32 v[134:135], v[134:135], s[26:27], v[128:129] op_sel_hi:[1,0,0] neg_lo:[1,0,0] neg_hi:[1,0,0]
	v_pk_mul_f32 v[108:109], v[96:97], v[108:109]
	v_pk_mul_f32 v[134:135], v[106:107], v[134:135]
	v_exp_f32_e32 v108, v108
	v_exp_f32_e32 v134, v134
	v_exp_f32_e32 v135, v135
	v_exp_f32_e32 v109, v109
	v_pk_mul_f32 v[136:137], v[30:31], v[102:103]
	v_pk_mul_f32 v[142:143], v[28:29], v[98:99]
	v_pk_add_f32 v[134:135], v[134:135], 1.0 op_sel_hi:[1,0]
	v_pk_add_f32 v[108:109], v[108:109], 1.0 op_sel_hi:[1,0]
	v_rcp_f32_e32 v134, v134
	v_rcp_f32_e32 v135, v135
	v_rcp_f32_e32 v108, v108
	v_rcp_f32_e32 v109, v109
	v_mov_b64_e32 v[146:147], v[160:161]
	v_pk_mul_f32 v[106:107], v[106:107], v[134:135]
	v_pk_mul_f32 v[134:135], v[16:17], v[90:91]
	v_pk_mul_f32 v[96:97], v[96:97], v[108:109]
	s_nop 0
	v_lshlrev_b32_e32 v43, 16, v94
	v_and_b32_e32 v94, 0xffff0000, v94
	v_lshlrev_b32_e32 v108, 16, v95
	v_and_b32_e32 v95, 0xffff0000, v95
	v_mul_f32_e32 v94, v107, v94
	v_mul_f32_e32 v95, v97, v95
	v_mul_f32_e32 v43, v106, v43
	v_mul_f32_e32 v96, v96, v108
	v_cvt_pk_bf16_f32 v94, v43, v94
	v_cvt_pk_bf16_f32 v95, v96, v95
	global_store_dwordx2 v[116:117], v[94:95], off offset:2560
	v_mov_b64_e32 v[106:107], v[186:187]
	v_pk_mul_f32 v[108:109], v[6:7], v[84:85]
	v_pk_mul_f32 v[116:117], v[4:5], v[82:83]
	v_lshlrev_b32_e32 v94, 16, v124
	v_and_b32_e32 v95, 0xffff0000, v124
	v_lshlrev_b32_e32 v96, 16, v125
	v_and_b32_e32 v97, 0xffff0000, v125
	v_pk_mul_f32 v[124:125], v[18:19], v[92:93]
	v_pk_fma_f32 v[108:109], v[2:3], v[126:127], v[108:109]
	v_pk_fma_f32 v[116:117], v[0:1], v[122:123], v[116:117]
	v_pk_fma_f32 v[122:123], v[14:15], v[120:121], v[124:125]
	v_pk_fma_f32 v[124:125], v[12:13], v[118:119], v[134:135]
	v_pk_fma_f32 v[108:109], v[10:11], v[74:75], v[108:109]
	v_pk_fma_f32 v[116:117], v[8:9], v[70:71], v[116:117]
	v_pk_fma_f32 v[126:127], v[26:27], v[132:133], v[136:137]
	v_pk_fma_f32 v[134:135], v[24:25], v[130:131], v[142:143]
	v_pk_fma_f32 v[122:123], v[22:23], v[88:89], v[122:123]
	v_pk_fma_f32 v[124:125], v[20:21], v[86:87], v[124:125]
	v_pk_add_f32 v[108:109], v[38:39], v[108:109]
	v_pk_add_f32 v[116:117], v[36:37], v[116:117]
	v_pk_fma_f32 v[126:127], v[34:35], v[96:97], v[126:127]
	v_pk_fma_f32 v[134:135], v[32:33], v[94:95], v[134:135]
	v_pk_add_f32 v[108:109], v[122:123], v[108:109]
	v_pk_add_f32 v[116:117], v[124:125], v[116:117]
	v_pk_add_f32 v[108:109], v[126:127], v[108:109]
	v_pk_add_f32 v[116:117], v[134:135], v[116:117]
	v_pk_mul_f32 v[122:123], v[108:109], v[108:109]
	v_pk_mul_f32 v[124:125], v[116:117], v[116:117]
	v_pk_fma_f32 v[122:123], v[122:123], s[26:27], v[128:129] op_sel_hi:[1,0,0] neg_lo:[1,0,0] neg_hi:[1,0,0]
	v_pk_fma_f32 v[124:125], v[124:125], s[26:27], v[128:129] op_sel_hi:[1,0,0] neg_lo:[1,0,0] neg_hi:[1,0,0]
	v_pk_mul_f32 v[122:123], v[108:109], v[122:123]
	v_pk_mul_f32 v[124:125], v[116:117], v[124:125]
	v_exp_f32_e32 v122, v122
	v_exp_f32_e32 v124, v124
	v_exp_f32_e32 v125, v125
	v_exp_f32_e32 v123, v123
	v_pk_mul_f32 v[126:127], v[30:31], v[114:115]
	v_pk_mul_f32 v[134:135], v[28:29], v[112:113]
	v_pk_add_f32 v[124:125], v[124:125], 1.0 op_sel_hi:[1,0]
	v_pk_add_f32 v[122:123], v[122:123], 1.0 op_sel_hi:[1,0]
	v_rcp_f32_e32 v124, v124
	v_rcp_f32_e32 v125, v125
	v_rcp_f32_e32 v122, v122
	v_rcp_f32_e32 v123, v123
	v_pk_mul_f32 v[116:117], v[116:117], v[124:125]
	v_pk_mul_f32 v[124:125], v[16:17], v[98:99]
	v_pk_mul_f32 v[108:109], v[108:109], v[122:123]
	s_nop 0
	v_lshlrev_b32_e32 v43, 16, v106
	v_and_b32_e32 v106, 0xffff0000, v106
	v_lshlrev_b32_e32 v122, 16, v107
	v_and_b32_e32 v107, 0xffff0000, v107
	v_mul_f32_e32 v106, v117, v106
	v_mul_f32_e32 v107, v109, v107
	v_mul_f32_e32 v43, v116, v43
	v_mul_f32_e32 v108, v108, v122
	v_cvt_pk_bf16_f32 v106, v43, v106
	v_cvt_pk_bf16_f32 v107, v108, v107
	global_store_dwordx2 v[110:111], v[106:107], off offset:2560
	v_mov_b64_e32 v[110:111], v[188:189]
	v_lshlrev_b32_e32 v106, 16, v104
	v_and_b32_e32 v107, 0xffff0000, v104
	v_lshlrev_b32_e32 v108, 16, v105
	v_and_b32_e32 v109, 0xffff0000, v105
	v_pk_mul_f32 v[104:105], v[6:7], v[92:93]
	v_pk_mul_f32 v[116:117], v[4:5], v[90:91]
	v_pk_mul_f32 v[122:123], v[18:19], v[102:103]
	v_pk_fma_f32 v[104:105], v[2:3], v[120:121], v[104:105]
	v_pk_fma_f32 v[116:117], v[0:1], v[118:119], v[116:117]
	v_pk_fma_f32 v[118:119], v[14:15], v[132:133], v[122:123]
	v_pk_fma_f32 v[104:105], v[10:11], v[88:89], v[104:105]
	v_pk_fma_f32 v[120:121], v[12:13], v[130:131], v[124:125]
	v_pk_fma_f32 v[122:123], v[26:27], v[140:141], v[126:127]
	v_pk_fma_f32 v[116:117], v[8:9], v[86:87], v[116:117]
	v_pk_fma_f32 v[118:119], v[22:23], v[96:97], v[118:119]
	v_pk_add_f32 v[104:105], v[38:39], v[104:105]
	v_pk_fma_f32 v[124:125], v[24:25], v[138:139], v[134:135]
	v_pk_fma_f32 v[120:121], v[20:21], v[94:95], v[120:121]
	v_pk_fma_f32 v[122:123], v[34:35], v[108:109], v[122:123]
	v_pk_add_f32 v[116:117], v[36:37], v[116:117]
	v_pk_add_f32 v[104:105], v[118:119], v[104:105]
	v_pk_fma_f32 v[124:125], v[32:33], v[106:107], v[124:125]
	v_pk_add_f32 v[116:117], v[120:121], v[116:117]
	v_pk_add_f32 v[104:105], v[122:123], v[104:105]
	v_pk_add_f32 v[116:117], v[124:125], v[116:117]
	v_pk_mul_f32 v[118:119], v[104:105], v[104:105]
	v_pk_mul_f32 v[120:121], v[116:117], v[116:117]
	v_pk_fma_f32 v[118:119], v[118:119], s[26:27], v[128:129] op_sel_hi:[1,0,0] neg_lo:[1,0,0] neg_hi:[1,0,0]
	v_pk_fma_f32 v[120:121], v[120:121], s[26:27], v[128:129] op_sel_hi:[1,0,0] neg_lo:[1,0,0] neg_hi:[1,0,0]
	v_pk_mul_f32 v[118:119], v[104:105], v[118:119]
	v_pk_mul_f32 v[120:121], v[116:117], v[120:121]
	v_exp_f32_e32 v118, v118
	v_exp_f32_e32 v119, v119
	v_exp_f32_e32 v120, v120
	v_exp_f32_e32 v121, v121
	v_mov_b64_e32 v[124:125], v[162:163]
	v_pk_add_f32 v[118:119], v[118:119], 1.0 op_sel_hi:[1,0]
	v_pk_add_f32 v[120:121], v[120:121], 1.0 op_sel_hi:[1,0]
	v_rcp_f32_e32 v118, v118
	v_rcp_f32_e32 v119, v119
	v_rcp_f32_e32 v120, v120
	v_rcp_f32_e32 v121, v121
	v_pk_mul_f32 v[104:105], v[104:105], v[118:119]
	v_pk_mul_f32 v[116:117], v[116:117], v[120:121]
	s_nop 0
	v_lshlrev_b32_e32 v118, 16, v111
	v_and_b32_e32 v111, 0xffff0000, v111
	v_lshlrev_b32_e32 v43, 16, v110
	v_and_b32_e32 v110, 0xffff0000, v110
	v_mul_f32_e32 v105, v105, v111
	v_mul_f32_e32 v43, v116, v43
	v_mul_f32_e32 v110, v117, v110
	v_mul_f32_e32 v116, v104, v118
	v_cvt_pk_bf16_f32 v104, v43, v110
	v_cvt_pk_bf16_f32 v105, v116, v105
	global_store_dwordx2 v[100:101], v[104:105], off offset:2560
	v_mov_b64_e32 v[104:105], v[164:165]

.LBB0_959:
	s_or_b64 exec, exec, s[10:11]
	v_add_co_u32_e32 v130, vcc, s61, v128
	v_lshlrev_b32_e32 v142, 16, v118
	s_nop 0
	v_addc_co_u32_e32 v131, vcc, 0, v129, vcc
	global_load_dwordx2 v[138:139], v[130:131], off offset:3584
	v_lshl_add_u64 v[178:179], v[116:117], 0, s[98:99]
	v_lshl_add_u64 v[180:181], v[110:111], 0, s[98:99]
	v_lshl_add_u64 v[182:183], v[100:101], 0, s[98:99]
	global_load_dwordx2 v[184:185], v[178:179], off offset:3584
	global_load_dwordx2 v[186:187], v[180:181], off offset:3584
	global_load_dwordx2 v[188:189], v[182:183], off offset:3584
	v_and_b32_e32 v143, 0xffff0000, v118
	v_lshlrev_b32_e32 v144, 16, v119
	v_and_b32_e32 v145, 0xffff0000, v119
	v_pk_mul_f32 v[118:119], v[6:7], v[64:65]
	v_pk_mul_f32 v[156:157], v[4:5], v[62:63]
	v_pk_mul_f32 v[158:159], v[18:19], v[68:69]
	v_pk_fma_f32 v[118:119], v[2:3], v[76:77], v[118:119]
	v_lshlrev_b32_e32 v136, 16, v123
	v_and_b32_e32 v137, 0xffff0000, v123
	v_pk_mul_f32 v[160:161], v[16:17], v[66:67]
	v_pk_mul_f32 v[162:163], v[30:31], v[74:75]
	v_pk_fma_f32 v[156:157], v[0:1], v[72:73], v[156:157]
	v_pk_fma_f32 v[158:159], v[14:15], v[80:81], v[158:159]
	v_pk_fma_f32 v[118:119], v[10:11], v[144:145], v[118:119]
	v_lshlrev_b32_e32 v134, 16, v122
	v_and_b32_e32 v135, 0xffff0000, v122
	v_lshlrev_b32_e32 v122, 16, v126
	v_and_b32_e32 v123, 0xffff0000, v126
	v_lshlrev_b32_e32 v126, 16, v127
	v_and_b32_e32 v127, 0xffff0000, v127
	v_pk_mul_f32 v[164:165], v[28:29], v[70:71]
	v_pk_fma_f32 v[160:161], v[12:13], v[78:79], v[160:161]
	v_pk_fma_f32 v[162:163], v[26:27], v[84:85], v[162:163]
	v_pk_fma_f32 v[156:157], v[8:9], v[142:143], v[156:157]
	v_pk_fma_f32 v[158:159], v[22:23], v[136:137], v[158:159]
	v_pk_add_f32 v[118:119], v[38:39], v[118:119]
	v_pk_fma_f32 v[164:165], v[24:25], v[82:83], v[164:165]
	v_pk_fma_f32 v[160:161], v[20:21], v[134:135], v[160:161]
	v_pk_fma_f32 v[162:163], v[34:35], v[126:127], v[162:163]
	v_pk_add_f32 v[156:157], v[36:37], v[156:157]
	v_pk_add_f32 v[118:119], v[118:119], v[158:159]
	v_pk_fma_f32 v[164:165], v[32:33], v[122:123], v[164:165]
	v_pk_add_f32 v[156:157], v[156:157], v[160:161]
	v_pk_add_f32 v[118:119], v[118:119], v[162:163]
	v_mov_b64_e32 v[154:155], s[28:29]
	v_pk_add_f32 v[156:157], v[156:157], v[164:165]
	v_pk_mul_f32 v[158:159], v[118:119], v[118:119]
	v_pk_mul_f32 v[160:161], v[156:157], v[156:157]
	v_pk_fma_f32 v[158:159], v[158:159], s[26:27], v[154:155] op_sel_hi:[1,0,0] neg_lo:[1,0,0] neg_hi:[1,0,0]
	v_pk_fma_f32 v[160:161], v[160:161], s[26:27], v[154:155] op_sel_hi:[1,0,0] neg_lo:[1,0,0] neg_hi:[1,0,0]
	v_pk_mul_f32 v[158:159], v[118:119], v[158:159]
	v_pk_mul_f32 v[160:161], v[156:157], v[160:161]
	v_exp_f32_e32 v158, v158
	v_exp_f32_e32 v159, v159
	v_exp_f32_e32 v160, v160
	v_exp_f32_e32 v161, v161
	v_add_co_u32_e32 v162, vcc, s61, v116
	v_pk_add_f32 v[158:159], v[158:159], 1.0 op_sel_hi:[1,0]
	v_pk_add_f32 v[160:161], v[160:161], 1.0 op_sel_hi:[1,0]
	v_rcp_f32_e32 v158, v158
	v_rcp_f32_e32 v159, v159
	v_rcp_f32_e32 v160, v160
	v_rcp_f32_e32 v161, v161
	v_addc_co_u32_e32 v163, vcc, 0, v117, vcc
	v_pk_mul_f32 v[118:119], v[118:119], v[158:159]
	v_pk_mul_f32 v[156:157], v[156:157], v[160:161]
	v_pk_mul_f32 v[160:161], v[16:17], v[70:71]
	v_pk_mul_f32 v[164:165], v[30:31], v[88:89]
	v_pk_mul_f32 v[170:171], v[28:29], v[86:87]
	v_pk_fma_f32 v[160:161], v[12:13], v[82:83], v[160:161]
	v_pk_fma_f32 v[170:171], v[24:25], v[90:91], v[170:171]
	v_pk_fma_f32 v[164:165], v[26:27], v[92:93], v[164:165]
	v_pk_fma_f32 v[160:161], v[20:21], v[122:123], v[160:161]
	v_pk_mul_f32 v[172:173], v[28:29], v[94:95]
	v_pk_mul_f32 v[174:175], v[28:29], v[106:107]
	v_pk_fma_f32 v[172:173], v[24:25], v[98:99], v[172:173]
	v_pk_fma_f32 v[174:175], v[24:25], v[112:113], v[174:175]
	s_waitcnt vmcnt(0) lgkmcnt(0)
	v_lshlrev_b32_e32 v158, 16, v139
	v_and_b32_e32 v139, 0xffff0000, v139
	v_lshlrev_b32_e32 v43, 16, v138
	v_and_b32_e32 v138, 0xffff0000, v138
	v_mul_f32_e32 v119, v119, v139
	v_mul_f32_e32 v43, v156, v43
	v_mul_f32_e32 v138, v157, v138
	v_mul_f32_e32 v156, v118, v158
	v_cvt_pk_bf16_f32 v118, v43, v138
	v_cvt_pk_bf16_f32 v119, v156, v119
	global_store_dwordx2 v[130:131], v[118:119], off offset:3584
	v_mov_b64_e32 v[130:131], v[184:185]
	v_pk_mul_f32 v[138:139], v[6:7], v[68:69]
	v_pk_mul_f32 v[156:157], v[4:5], v[66:67]
	v_pk_mul_f32 v[158:159], v[18:19], v[74:75]
	v_pk_fma_f32 v[156:157], v[0:1], v[78:79], v[156:157]
	v_pk_fma_f32 v[138:139], v[2:3], v[80:81], v[138:139]
	v_pk_fma_f32 v[158:159], v[14:15], v[84:85], v[158:159]
	v_pk_fma_f32 v[138:139], v[10:11], v[136:137], v[138:139]
	v_pk_fma_f32 v[156:157], v[8:9], v[134:135], v[156:157]
	v_lshlrev_b32_e32 v118, 16, v120
	v_and_b32_e32 v119, 0xffff0000, v120
	v_lshlrev_b32_e32 v120, 16, v121
	v_and_b32_e32 v121, 0xffff0000, v121
	v_pk_fma_f32 v[158:159], v[22:23], v[126:127], v[158:159]
	v_pk_add_f32 v[156:157], v[36:37], v[156:157]
	v_pk_add_f32 v[138:139], v[38:39], v[138:139]
	v_pk_fma_f32 v[164:165], v[34:35], v[120:121], v[164:165]
	v_pk_fma_f32 v[170:171], v[32:33], v[118:119], v[170:171]
	v_pk_add_f32 v[138:139], v[138:139], v[158:159]
	v_pk_add_f32 v[156:157], v[156:157], v[160:161]
	v_pk_add_f32 v[138:139], v[138:139], v[164:165]
	v_pk_add_f32 v[156:157], v[156:157], v[170:171]
	v_pk_mul_f32 v[158:159], v[138:139], v[138:139]
	v_pk_mul_f32 v[160:161], v[156:157], v[156:157]
	v_pk_fma_f32 v[158:159], v[158:159], s[26:27], v[154:155] op_sel_hi:[1,0,0] neg_lo:[1,0,0] neg_hi:[1,0,0]
	v_pk_fma_f32 v[160:161], v[160:161], s[26:27], v[154:155] op_sel_hi:[1,0,0] neg_lo:[1,0,0] neg_hi:[1,0,0]
	v_pk_mul_f32 v[158:159], v[138:139], v[158:159]
	v_pk_mul_f32 v[160:161], v[156:157], v[160:161]
	v_exp_f32_e32 v158, v158
	v_exp_f32_e32 v160, v160
	v_exp_f32_e32 v161, v161
	v_exp_f32_e32 v159, v159
	v_add_co_u32_e32 v164, vcc, s61, v110
	v_pk_add_f32 v[160:161], v[160:161], 1.0 op_sel_hi:[1,0]
	v_pk_add_f32 v[158:159], v[158:159], 1.0 op_sel_hi:[1,0]
	v_rcp_f32_e32 v160, v160
	v_rcp_f32_e32 v161, v161
	v_rcp_f32_e32 v158, v158
	v_rcp_f32_e32 v159, v159
	v_addc_co_u32_e32 v165, vcc, 0, v111, vcc
	v_pk_mul_f32 v[156:157], v[156:157], v[160:161]
	v_pk_mul_f32 v[138:139], v[138:139], v[158:159]
	v_pk_mul_f32 v[160:161], v[18:19], v[88:89]
	v_pk_mul_f32 v[170:171], v[30:31], v[96:97]
	v_pk_fma_f32 v[160:161], v[14:15], v[92:93], v[160:161]
	v_pk_fma_f32 v[170:171], v[26:27], v[102:103], v[170:171]
	v_pk_fma_f32 v[160:161], v[22:23], v[120:121], v[160:161]
	s_nop 0
	v_lshlrev_b32_e32 v43, 16, v130
	v_and_b32_e32 v130, 0xffff0000, v130
	v_lshlrev_b32_e32 v158, 16, v131
	v_and_b32_e32 v131, 0xffff0000, v131
	v_mul_f32_e32 v130, v157, v130
	v_mul_f32_e32 v131, v139, v131
	v_mul_f32_e32 v43, v156, v43
	v_mul_f32_e32 v138, v138, v158
	v_cvt_pk_bf16_f32 v130, v43, v130
	v_cvt_pk_bf16_f32 v131, v138, v131
	global_store_dwordx2 v[162:163], v[130:131], off offset:3584
	v_mov_b64_e32 v[138:139], v[186:187]
	v_pk_mul_f32 v[156:157], v[6:7], v[74:75]
	v_pk_mul_f32 v[158:159], v[4:5], v[70:71]
	v_pk_mul_f32 v[162:163], v[16:17], v[86:87]
	v_pk_fma_f32 v[158:159], v[0:1], v[82:83], v[158:159]
	v_pk_fma_f32 v[156:157], v[2:3], v[84:85], v[156:157]
	v_pk_fma_f32 v[162:163], v[12:13], v[90:91], v[162:163]
	v_pk_fma_f32 v[156:157], v[10:11], v[126:127], v[156:157]
	v_pk_fma_f32 v[158:159], v[8:9], v[122:123], v[158:159]
	v_lshlrev_b32_e32 v130, 16, v132
	v_and_b32_e32 v131, 0xffff0000, v132
	v_lshlrev_b32_e32 v132, 16, v133
	v_and_b32_e32 v133, 0xffff0000, v133
	v_pk_fma_f32 v[162:163], v[20:21], v[118:119], v[162:163]
	v_pk_add_f32 v[158:159], v[36:37], v[158:159]
	v_pk_add_f32 v[156:157], v[38:39], v[156:157]
	v_pk_fma_f32 v[170:171], v[34:35], v[132:133], v[170:171]
	v_pk_fma_f32 v[172:173], v[32:33], v[130:131], v[172:173]
	v_pk_add_f32 v[156:157], v[156:157], v[160:161]
	v_pk_add_f32 v[158:159], v[158:159], v[162:163]
	v_pk_add_f32 v[156:157], v[156:157], v[170:171]
	v_pk_add_f32 v[158:159], v[158:159], v[172:173]
	v_pk_mul_f32 v[160:161], v[156:157], v[156:157]
	v_pk_mul_f32 v[162:163], v[158:159], v[158:159]
	v_pk_fma_f32 v[160:161], v[160:161], s[26:27], v[154:155] op_sel_hi:[1,0,0] neg_lo:[1,0,0] neg_hi:[1,0,0]
	v_pk_fma_f32 v[162:163], v[162:163], s[26:27], v[154:155] op_sel_hi:[1,0,0] neg_lo:[1,0,0] neg_hi:[1,0,0]
	v_pk_mul_f32 v[160:161], v[156:157], v[160:161]
	v_pk_mul_f32 v[162:163], v[158:159], v[162:163]
	v_exp_f32_e32 v160, v160
	v_exp_f32_e32 v162, v162
	v_exp_f32_e32 v163, v163
	v_exp_f32_e32 v161, v161
	v_add_co_u32_e32 v170, vcc, s61, v100
	v_pk_add_f32 v[162:163], v[162:163], 1.0 op_sel_hi:[1,0]
	v_pk_add_f32 v[160:161], v[160:161], 1.0 op_sel_hi:[1,0]
	v_rcp_f32_e32 v162, v162
	v_rcp_f32_e32 v163, v163
	v_rcp_f32_e32 v160, v160
	v_rcp_f32_e32 v161, v161
	v_addc_co_u32_e32 v171, vcc, 0, v101, vcc
	v_pk_mul_f32 v[158:159], v[158:159], v[162:163]
	v_pk_mul_f32 v[156:157], v[156:157], v[160:161]
	v_pk_mul_f32 v[162:163], v[18:19], v[96:97]
	v_pk_mul_f32 v[172:173], v[30:31], v[108:109]
	v_pk_fma_f32 v[162:163], v[14:15], v[102:103], v[162:163]
	v_pk_fma_f32 v[172:173], v[26:27], v[114:115], v[172:173]
	v_pk_fma_f32 v[162:163], v[22:23], v[132:133], v[162:163]
	s_nop 0
	v_lshlrev_b32_e32 v43, 16, v138
	v_and_b32_e32 v138, 0xffff0000, v138
	v_lshlrev_b32_e32 v160, 16, v139
	v_and_b32_e32 v139, 0xffff0000, v139
	v_mul_f32_e32 v138, v159, v138
	v_mul_f32_e32 v139, v157, v139
	v_mul_f32_e32 v43, v158, v43
	v_mul_f32_e32 v156, v156, v160
	v_cvt_pk_bf16_f32 v138, v43, v138
	v_cvt_pk_bf16_f32 v139, v156, v139
	global_store_dwordx2 v[164:165], v[138:139], off offset:3584
	v_mov_b64_e32 v[156:157], v[188:189]
	v_pk_mul_f32 v[158:159], v[6:7], v[88:89]
	v_pk_mul_f32 v[160:161], v[4:5], v[86:87]
	v_pk_mul_f32 v[164:165], v[16:17], v[94:95]
	v_pk_fma_f32 v[160:161], v[0:1], v[90:91], v[160:161]
	v_pk_fma_f32 v[158:159], v[2:3], v[92:93], v[158:159]
	v_pk_fma_f32 v[164:165], v[12:13], v[98:99], v[164:165]
	v_pk_fma_f32 v[158:159], v[10:11], v[120:121], v[158:159]
	v_pk_fma_f32 v[160:161], v[8:9], v[118:119], v[160:161]
	v_lshlrev_b32_e32 v138, 16, v140
	v_and_b32_e32 v139, 0xffff0000, v140
	v_lshlrev_b32_e32 v140, 16, v141
	v_and_b32_e32 v141, 0xffff0000, v141
	v_pk_fma_f32 v[164:165], v[20:21], v[130:131], v[164:165]
	v_pk_add_f32 v[160:161], v[36:37], v[160:161]
	v_pk_add_f32 v[158:159], v[38:39], v[158:159]
	v_pk_fma_f32 v[172:173], v[34:35], v[140:141], v[172:173]
	v_pk_fma_f32 v[174:175], v[32:33], v[138:139], v[174:175]
	v_pk_add_f32 v[158:159], v[158:159], v[162:163]
	v_pk_add_f32 v[160:161], v[160:161], v[164:165]
	v_pk_add_f32 v[158:159], v[158:159], v[172:173]
	v_pk_add_f32 v[160:161], v[160:161], v[174:175]
	v_pk_mul_f32 v[162:163], v[158:159], v[158:159]
	v_pk_mul_f32 v[164:165], v[160:161], v[160:161]
	v_add_u32_e32 v43, 1, v168
	v_pk_fma_f32 v[164:165], v[164:165], s[26:27], v[154:155] op_sel_hi:[1,0,0] neg_lo:[1,0,0] neg_hi:[1,0,0]
	v_pk_fma_f32 v[154:155], v[162:163], s[26:27], v[154:155] op_sel_hi:[1,0,0] neg_lo:[1,0,0] neg_hi:[1,0,0]
	v_pk_mul_f32 v[162:163], v[160:161], v[164:165]
	v_pk_mul_f32 v[154:155], v[158:159], v[154:155]
	v_exp_f32_e32 v162, v162
	v_exp_f32_e32 v154, v154
	v_exp_f32_e32 v155, v155
	v_exp_f32_e32 v163, v163
	v_cmp_lt_u32_e32 vcc, v43, v53
	v_pk_add_f32 v[154:155], v[154:155], 1.0 op_sel_hi:[1,0]
	v_pk_add_f32 v[162:163], v[162:163], 1.0 op_sel_hi:[1,0]
	v_rcp_f32_e32 v154, v154
	v_rcp_f32_e32 v155, v155
	v_rcp_f32_e32 v162, v162
	v_rcp_f32_e32 v163, v163
	v_pk_mul_f32 v[154:155], v[158:159], v[154:155]
	v_pk_mul_f32 v[160:161], v[160:161], v[162:163]
	s_nop 0
	v_lshlrev_b32_e32 v159, 16, v157
	v_and_b32_e32 v157, 0xffff0000, v157
	v_lshlrev_b32_e32 v158, 16, v156
	v_and_b32_e32 v156, 0xffff0000, v156
	v_mul_f32_e32 v155, v155, v157
	v_mul_f32_e32 v158, v160, v158
	v_mul_f32_e32 v156, v161, v156
	v_mul_f32_e32 v159, v154, v159
	v_cvt_pk_bf16_f32 v154, v158, v156
	v_cvt_pk_bf16_f32 v155, v159, v155
	global_store_dwordx2 v[170:171], v[154:155], off offset:3584
	s_and_saveexec_b64 s[36:37], vcc
	s_cbranch_execz .LBB0_969
	v_cmp_gt_u32_e64 s[10:11], 61, v168
	v_mov_b32_e32 v154, v42
	v_mov_b32_e32 v155, v42
	s_and_b64 s[4:5], s[6:7], s[10:11]
	v_mov_b64_e32 v[158:159], v[154:155]
	s_and_saveexec_b64 s[46:47], s[4:5]
	s_cbranch_execz .LBB0_962
	v_add_u32_e32 v43, s34, v52
	v_add_u32_e32 v72, 0xfffac200, v43
	v_mov_b32_e32 v73, v42
	v_lshl_add_u64 v[72:73], v[44:45], 0, v[72:73]
	global_load_dwordx2 v[158:159], v[72:73], off

.LBB0_968:
	s_or_b64 exec, exec, s[10:11]
	v_add_co_u32_e32 v90, vcc, s62, v128
	v_pk_mul_f32 v[98:99], v[2:3], v[64:65]
	s_nop 0
	v_addc_co_u32_e32 v91, vcc, 0, v129, vcc
	global_load_dwordx2 v[92:93], v[90:91], off offset:1024
	v_lshl_add_u64 v[178:179], v[116:117], 0, s[100:101]
	v_lshl_add_u64 v[180:181], v[110:111], 0, s[100:101]
	v_lshl_add_u64 v[182:183], v[100:101], 0, s[100:101]
	global_load_dwordx2 v[184:185], v[178:179], off offset:-3072
	global_load_dwordx2 v[186:187], v[180:181], off offset:-3072
	global_load_dwordx2 v[188:189], v[182:183], off offset:-3072
	v_pk_mul_f32 v[102:103], v[0:1], v[62:63]
	v_lshlrev_b32_e32 v72, 16, v148
	v_and_b32_e32 v73, 0xffff0000, v148
	v_lshlrev_b32_e32 v76, 16, v149
	v_and_b32_e32 v77, 0xffff0000, v149
	v_pk_mul_f32 v[112:113], v[14:15], v[68:69]
	v_pk_mul_f32 v[114:115], v[12:13], v[66:67]
	v_pk_fma_f32 v[98:99], v[6:7], v[144:145], v[98:99]
	v_pk_fma_f32 v[102:103], v[4:5], v[142:143], v[102:103]
	v_lshlrev_b32_e32 v78, 16, v152
	v_and_b32_e32 v79, 0xffff0000, v152
	v_lshlrev_b32_e32 v80, 16, v153
	v_and_b32_e32 v81, 0xffff0000, v153
	v_pk_mul_f32 v[148:149], v[26:27], v[74:75]
	v_pk_mul_f32 v[152:153], v[24:25], v[70:71]
	v_pk_fma_f32 v[112:113], v[18:19], v[136:137], v[112:113]
	v_pk_fma_f32 v[114:115], v[16:17], v[134:135], v[114:115]
	v_pk_fma_f32 v[98:99], v[10:11], v[76:77], v[98:99]
	v_pk_fma_f32 v[102:103], v[8:9], v[72:73], v[102:103]
	v_lshlrev_b32_e32 v82, 16, v150
	v_and_b32_e32 v83, 0xffff0000, v150
	v_lshlrev_b32_e32 v84, 16, v151
	v_and_b32_e32 v85, 0xffff0000, v151
	v_pk_fma_f32 v[148:149], v[30:31], v[126:127], v[148:149]
	v_pk_fma_f32 v[152:153], v[28:29], v[122:123], v[152:153]
	v_pk_fma_f32 v[112:113], v[22:23], v[80:81], v[112:113]
	v_pk_fma_f32 v[114:115], v[20:21], v[78:79], v[114:115]
	v_pk_add_f32 v[98:99], v[38:39], v[98:99]
	v_pk_add_f32 v[102:103], v[36:37], v[102:103]
	v_pk_fma_f32 v[148:149], v[34:35], v[84:85], v[148:149]
	v_pk_fma_f32 v[152:153], v[32:33], v[82:83], v[152:153]
	v_pk_add_f32 v[98:99], v[98:99], v[112:113]
	v_pk_add_f32 v[102:103], v[102:103], v[114:115]
	v_pk_add_f32 v[98:99], v[98:99], v[148:149]
	v_pk_add_f32 v[102:103], v[102:103], v[152:153]
	v_mov_b64_e32 v[150:151], s[28:29]
	v_pk_mul_f32 v[112:113], v[98:99], v[98:99]
	v_pk_mul_f32 v[114:115], v[102:103], v[102:103]
	v_pk_fma_f32 v[112:113], v[112:113], s[26:27], v[150:151] op_sel_hi:[1,0,0] neg_lo:[1,0,0] neg_hi:[1,0,0]
	v_pk_fma_f32 v[114:115], v[114:115], s[26:27], v[150:151] op_sel_hi:[1,0,0] neg_lo:[1,0,0] neg_hi:[1,0,0]
	v_pk_mul_f32 v[112:113], v[98:99], v[112:113]
	v_pk_mul_f32 v[114:115], v[102:103], v[114:115]
	v_exp_f32_e32 v112, v112
	v_exp_f32_e32 v114, v114
	v_exp_f32_e32 v115, v115
	v_exp_f32_e32 v113, v113
	v_add_co_u32_e32 v148, vcc, s62, v116
	v_pk_add_f32 v[114:115], v[114:115], 1.0 op_sel_hi:[1,0]
	v_pk_add_f32 v[112:113], v[112:113], 1.0 op_sel_hi:[1,0]
	v_rcp_f32_e32 v114, v114
	v_rcp_f32_e32 v115, v115
	v_rcp_f32_e32 v112, v112
	v_rcp_f32_e32 v113, v113
	v_addc_co_u32_e32 v149, vcc, 0, v117, vcc
	v_pk_mul_f32 v[102:103], v[102:103], v[114:115]
	v_pk_mul_f32 v[98:99], v[98:99], v[112:113]
	v_pk_mul_f32 v[114:115], v[14:15], v[74:75]
	v_pk_mul_f32 v[152:153], v[26:27], v[88:89]
	v_pk_mul_f32 v[170:171], v[24:25], v[86:87]
	v_pk_fma_f32 v[114:115], v[18:19], v[126:127], v[114:115]
	v_pk_fma_f32 v[152:153], v[30:31], v[120:121], v[152:153]
	v_pk_fma_f32 v[170:171], v[28:29], v[118:119], v[170:171]
	v_pk_fma_f32 v[114:115], v[22:23], v[84:85], v[114:115]
	v_pk_mul_f32 v[172:173], v[24:25], v[94:95]
	v_pk_mul_f32 v[174:175], v[26:27], v[108:109]
	v_pk_fma_f32 v[172:173], v[28:29], v[130:131], v[172:173]
	v_pk_mul_f32 v[176:177], v[24:25], v[106:107]
	s_waitcnt vmcnt(0) lgkmcnt(0)
	v_lshlrev_b32_e32 v43, 16, v92
	v_and_b32_e32 v92, 0xffff0000, v92
	v_lshlrev_b32_e32 v112, 16, v93
	v_and_b32_e32 v93, 0xffff0000, v93
	v_mul_f32_e32 v92, v103, v92
	v_mul_f32_e32 v93, v99, v93
	v_mul_f32_e32 v43, v102, v43
	v_mul_f32_e32 v98, v98, v112
	v_cvt_pk_bf16_f32 v92, v43, v92
	v_cvt_pk_bf16_f32 v93, v98, v93
	global_store_dwordx2 v[90:91], v[92:93], off offset:1024
	v_mov_b64_e32 v[98:99], v[184:185]
	v_pk_mul_f32 v[102:103], v[2:3], v[68:69]
	v_pk_mul_f32 v[112:113], v[0:1], v[66:67]
	v_lshlrev_b32_e32 v90, 16, v146
	v_and_b32_e32 v91, 0xffff0000, v146
	v_lshlrev_b32_e32 v92, 16, v147
	v_and_b32_e32 v93, 0xffff0000, v147
	v_pk_mul_f32 v[146:147], v[12:13], v[70:71]
	v_pk_fma_f32 v[102:103], v[6:7], v[136:137], v[102:103]
	v_pk_fma_f32 v[112:113], v[4:5], v[134:135], v[112:113]
	v_pk_fma_f32 v[146:147], v[16:17], v[122:123], v[146:147]
	v_pk_fma_f32 v[102:103], v[10:11], v[80:81], v[102:103]
	v_pk_fma_f32 v[112:113], v[8:9], v[78:79], v[112:113]
	v_pk_fma_f32 v[146:147], v[20:21], v[82:83], v[146:147]
	v_pk_add_f32 v[102:103], v[38:39], v[102:103]
	v_pk_add_f32 v[112:113], v[36:37], v[112:113]
	v_pk_fma_f32 v[152:153], v[34:35], v[92:93], v[152:153]
	v_pk_fma_f32 v[170:171], v[32:33], v[90:91], v[170:171]
	v_pk_add_f32 v[102:103], v[102:103], v[114:115]
	v_pk_add_f32 v[112:113], v[112:113], v[146:147]
	v_pk_add_f32 v[102:103], v[102:103], v[152:153]
	v_pk_add_f32 v[112:113], v[112:113], v[170:171]
	v_pk_mul_f32 v[114:115], v[102:103], v[102:103]
	v_pk_mul_f32 v[146:147], v[112:113], v[112:113]
	v_pk_fma_f32 v[114:115], v[114:115], s[26:27], v[150:151] op_sel_hi:[1,0,0] neg_lo:[1,0,0] neg_hi:[1,0,0]
	v_pk_fma_f32 v[146:147], v[146:147], s[26:27], v[150:151] op_sel_hi:[1,0,0] neg_lo:[1,0,0] neg_hi:[1,0,0]
	v_pk_mul_f32 v[114:115], v[102:103], v[114:115]
	v_pk_mul_f32 v[146:147], v[112:113], v[146:147]
	v_exp_f32_e32 v114, v114
	v_exp_f32_e32 v146, v146
	v_exp_f32_e32 v147, v147
	v_exp_f32_e32 v115, v115
	v_add_co_u32_e32 v152, vcc, s62, v110
	v_pk_add_f32 v[146:147], v[146:147], 1.0 op_sel_hi:[1,0]
	v_pk_add_f32 v[114:115], v[114:115], 1.0 op_sel_hi:[1,0]
	v_rcp_f32_e32 v146, v146
	v_rcp_f32_e32 v147, v147
	v_rcp_f32_e32 v114, v114
	v_rcp_f32_e32 v115, v115
	v_addc_co_u32_e32 v153, vcc, 0, v111, vcc
	v_pk_mul_f32 v[112:113], v[112:113], v[146:147]
	v_pk_mul_f32 v[102:103], v[102:103], v[114:115]
	v_pk_mul_f32 v[146:147], v[14:15], v[88:89]
	v_pk_mul_f32 v[170:171], v[26:27], v[96:97]
	v_pk_fma_f32 v[146:147], v[18:19], v[120:121], v[146:147]
	v_pk_fma_f32 v[170:171], v[30:31], v[132:133], v[170:171]
	v_pk_fma_f32 v[146:147], v[22:23], v[92:93], v[146:147]
	s_nop 0
	v_lshlrev_b32_e32 v43, 16, v98
	v_and_b32_e32 v98, 0xffff0000, v98
	v_lshlrev_b32_e32 v114, 16, v99
	v_and_b32_e32 v99, 0xffff0000, v99
	v_mul_f32_e32 v98, v113, v98
	v_mul_f32_e32 v99, v103, v99
	v_mul_f32_e32 v43, v112, v43
	v_mul_f32_e32 v102, v102, v114
	v_cvt_pk_bf16_f32 v98, v43, v98
	v_cvt_pk_bf16_f32 v99, v102, v99
	global_store_dwordx2 v[148:149], v[98:99], off offset:1024
	v_mov_b64_e32 v[112:113], v[186:187]
	v_lshlrev_b32_e32 v98, 16, v124
	v_and_b32_e32 v99, 0xffff0000, v124
	v_lshlrev_b32_e32 v102, 16, v125
	v_and_b32_e32 v103, 0xffff0000, v125
	v_pk_mul_f32 v[114:115], v[2:3], v[74:75]
	v_pk_mul_f32 v[124:125], v[0:1], v[70:71]
	v_pk_mul_f32 v[148:149], v[12:13], v[86:87]
	v_pk_fma_f32 v[114:115], v[6:7], v[126:127], v[114:115]
	v_pk_fma_f32 v[124:125], v[4:5], v[122:123], v[124:125]
	v_pk_fma_f32 v[148:149], v[16:17], v[118:119], v[148:149]
	v_pk_fma_f32 v[114:115], v[10:11], v[84:85], v[114:115]
	v_pk_fma_f32 v[124:125], v[8:9], v[82:83], v[124:125]
	v_pk_fma_f32 v[148:149], v[20:21], v[90:91], v[148:149]
	v_pk_add_f32 v[114:115], v[38:39], v[114:115]
	v_pk_add_f32 v[124:125], v[36:37], v[124:125]
	v_pk_fma_f32 v[170:171], v[34:35], v[102:103], v[170:171]
	v_pk_fma_f32 v[172:173], v[32:33], v[98:99], v[172:173]
	v_pk_add_f32 v[114:115], v[114:115], v[146:147]
	v_pk_add_f32 v[124:125], v[124:125], v[148:149]
	v_pk_add_f32 v[114:115], v[114:115], v[170:171]
	v_pk_add_f32 v[124:125], v[124:125], v[172:173]
	v_pk_mul_f32 v[146:147], v[114:115], v[114:115]
	v_pk_mul_f32 v[148:149], v[124:125], v[124:125]
	v_pk_fma_f32 v[146:147], v[146:147], s[26:27], v[150:151] op_sel_hi:[1,0,0] neg_lo:[1,0,0] neg_hi:[1,0,0]
	v_pk_fma_f32 v[148:149], v[148:149], s[26:27], v[150:151] op_sel_hi:[1,0,0] neg_lo:[1,0,0] neg_hi:[1,0,0]
	v_pk_mul_f32 v[146:147], v[114:115], v[146:147]
	v_pk_mul_f32 v[148:149], v[124:125], v[148:149]
	v_exp_f32_e32 v146, v146
	v_exp_f32_e32 v148, v148
	v_exp_f32_e32 v149, v149
	v_exp_f32_e32 v147, v147
	v_add_co_u32_e32 v170, vcc, s62, v100
	v_pk_add_f32 v[148:149], v[148:149], 1.0 op_sel_hi:[1,0]
	v_pk_add_f32 v[146:147], v[146:147], 1.0 op_sel_hi:[1,0]
	v_rcp_f32_e32 v148, v148
	v_rcp_f32_e32 v149, v149
	v_rcp_f32_e32 v146, v146
	v_rcp_f32_e32 v147, v147
	v_addc_co_u32_e32 v171, vcc, 0, v101, vcc
	v_pk_mul_f32 v[124:125], v[124:125], v[148:149]
	v_pk_mul_f32 v[114:115], v[114:115], v[146:147]
	v_mov_b64_e32 v[148:149], v[158:159]
	v_pk_fma_f32 v[158:159], v[30:31], v[140:141], v[174:175]
	v_pk_fma_f32 v[174:175], v[28:29], v[138:139], v[176:177]
	s_nop 0
	v_lshlrev_b32_e32 v43, 16, v112
	v_and_b32_e32 v112, 0xffff0000, v112
	v_lshlrev_b32_e32 v146, 16, v113
	v_and_b32_e32 v113, 0xffff0000, v113
	v_mul_f32_e32 v112, v125, v112
	v_mul_f32_e32 v113, v115, v113
	v_mul_f32_e32 v43, v124, v43
	v_mul_f32_e32 v114, v114, v146
	v_cvt_pk_bf16_f32 v112, v43, v112
	v_cvt_pk_bf16_f32 v113, v114, v113
	global_store_dwordx2 v[152:153], v[112:113], off offset:1024
	v_mov_b64_e32 v[172:173], v[188:189]
	v_lshlrev_b32_e32 v112, 16, v104
	v_and_b32_e32 v113, 0xffff0000, v104
	v_lshlrev_b32_e32 v114, 16, v105
	v_and_b32_e32 v115, 0xffff0000, v105
	v_pk_mul_f32 v[104:105], v[2:3], v[88:89]
	v_pk_mul_f32 v[124:125], v[0:1], v[86:87]
	v_pk_mul_f32 v[146:147], v[14:15], v[96:97]
	v_pk_mul_f32 v[152:153], v[12:13], v[94:95]
	v_pk_fma_f32 v[104:105], v[6:7], v[120:121], v[104:105]
	v_pk_fma_f32 v[124:125], v[4:5], v[118:119], v[124:125]
	v_pk_fma_f32 v[146:147], v[18:19], v[132:133], v[146:147]
	v_pk_fma_f32 v[152:153], v[16:17], v[130:131], v[152:153]
	v_pk_fma_f32 v[104:105], v[10:11], v[92:93], v[104:105]
	v_pk_fma_f32 v[124:125], v[8:9], v[90:91], v[124:125]
	v_pk_fma_f32 v[146:147], v[22:23], v[102:103], v[146:147]
	v_pk_fma_f32 v[152:153], v[20:21], v[98:99], v[152:153]
	v_pk_add_f32 v[104:105], v[38:39], v[104:105]
	v_pk_add_f32 v[124:125], v[36:37], v[124:125]
	v_pk_fma_f32 v[158:159], v[34:35], v[114:115], v[158:159]
	v_pk_fma_f32 v[174:175], v[32:33], v[112:113], v[174:175]
	v_pk_add_f32 v[104:105], v[104:105], v[146:147]
	v_pk_add_f32 v[124:125], v[124:125], v[152:153]
	v_pk_add_f32 v[104:105], v[104:105], v[158:159]
	v_pk_add_f32 v[158:159], v[124:125], v[174:175]
	v_pk_mul_f32 v[124:125], v[104:105], v[104:105]
	v_pk_mul_f32 v[146:147], v[158:159], v[158:159]
	v_pk_fma_f32 v[124:125], v[124:125], s[26:27], v[150:151] op_sel_hi:[1,0,0] neg_lo:[1,0,0] neg_hi:[1,0,0]
	v_pk_fma_f32 v[146:147], v[146:147], s[26:27], v[150:151] op_sel_hi:[1,0,0] neg_lo:[1,0,0] neg_hi:[1,0,0]
	v_pk_mul_f32 v[124:125], v[104:105], v[124:125]
	v_pk_mul_f32 v[146:147], v[158:159], v[146:147]
	v_exp_f32_e32 v124, v124
	v_exp_f32_e32 v146, v146
	v_exp_f32_e32 v147, v147
	v_exp_f32_e32 v125, v125
	v_mov_b64_e32 v[152:153], v[154:155]
	v_mov_b64_e32 v[150:151], v[156:157]
	v_pk_add_f32 v[146:147], v[146:147], 1.0 op_sel_hi:[1,0]
	v_pk_add_f32 v[124:125], v[124:125], 1.0 op_sel_hi:[1,0]
	v_rcp_f32_e32 v154, v146
	v_rcp_f32_e32 v155, v147
	v_rcp_f32_e32 v156, v124
	v_rcp_f32_e32 v157, v125
	v_mov_b64_e32 v[146:147], v[160:161]
	v_pk_mul_f32 v[154:155], v[158:159], v[154:155]
	v_mov_b64_e32 v[124:125], v[162:163]
	v_pk_mul_f32 v[104:105], v[104:105], v[156:157]
	s_nop 0
	v_and_b32_e32 v158, 0xffff0000, v173
	v_lshlrev_b32_e32 v43, 16, v172
	v_and_b32_e32 v156, 0xffff0000, v172
	v_lshlrev_b32_e32 v157, 16, v173
	v_mul_f32_e32 v105, v105, v158
	v_mul_f32_e32 v43, v154, v43
	v_mul_f32_e32 v154, v155, v156
	v_mul_f32_e32 v155, v104, v157
	v_cvt_pk_bf16_f32 v104, v43, v154
	v_cvt_pk_bf16_f32 v105, v155, v105
	global_store_dwordx2 v[170:171], v[104:105], off offset:1024
	v_mov_b64_e32 v[104:105], v[164:165]
